# super-phases 1 and 3: MFMA-opening barrier issued after the block's first 4 MFMAs, on top of v56
# speedup vs baseline: 1.0026x; 1.0026x over previous
.LBB0_233:
	ds_read_b128 v[130:133], v213
	ds_read_b128 v[134:137], v214
	ds_read_b128 v[138:141], v215
	ds_read_b128 v[142:145], v216
	ds_read_b128 v[146:149], v217
	ds_read_b128 v[150:153], v218
	ds_read_b128 v[154:157], v219
	ds_read_b128 v[158:161], v220
	s_add_i32 s4, s33, 0xffffe080
	s_cmp_eq_u32 s58, 12
	s_cselect_b32 s61, s18, s4
	s_cselect_b32 s60, s19, s57
	s_add_i32 s59, s61, 0x80
	s_mov_b32 s4, s70
	s_mov_b32 m0, s38
	ds_read_b128 v[162:165], v221
	ds_read_b128 v[166:169], v221 offset:2048
	ds_read_b128 v[170:173], v222
	ds_read_b128 v[174:177], v222 offset:2048
	ds_read_b128 v[178:181], v221 offset:4096
	ds_read_b128 v[182:185], v221 offset:6144
	ds_read_b128 v[186:189], v222 offset:4096
	ds_read_b128 v[190:193], v222 offset:6144
	buffer_load_dwordx4 v207, s[4:7], s33 offen lds
	s_mov_b32 m0, s41
	s_nop 0
	buffer_load_dwordx4 v209, s[4:7], s33 offen lds
	s_waitcnt vmcnt(8)
	s_waitcnt lgkmcnt(0)
	s_setprio 1
	v_mfma_f32_16x16x32_bf16 v[114:117], v[130:133], v[162:165], v[114:117]
	v_mfma_f32_16x16x32_bf16 v[110:113], v[138:141], v[162:165], v[110:113]
	v_mfma_f32_16x16x32_bf16 v[106:109], v[130:133], v[166:169], v[106:109]
	v_mfma_f32_16x16x32_bf16 v[102:105], v[138:141], v[166:169], v[102:105]
	s_barrier
	v_mfma_f32_16x16x32_bf16 v[98:101], v[130:133], v[178:181], v[98:101]
	v_mfma_f32_16x16x32_bf16 v[94:97], v[138:141], v[178:181], v[94:97]
	v_mfma_f32_16x16x32_bf16 v[90:93], v[130:133], v[182:185], v[90:93]
	v_mfma_f32_16x16x32_bf16 v[86:89], v[138:141], v[182:185], v[86:89]
	v_mfma_f32_16x16x32_bf16 v[114:117], v[134:137], v[170:173], v[114:117]
	v_mfma_f32_16x16x32_bf16 v[110:113], v[142:145], v[170:173], v[110:113]
	v_mfma_f32_16x16x32_bf16 v[106:109], v[134:137], v[174:177], v[106:109]
	v_mfma_f32_16x16x32_bf16 v[102:105], v[142:145], v[174:177], v[102:105]
	v_mfma_f32_16x16x32_bf16 v[98:101], v[134:137], v[186:189], v[98:101]
	v_mfma_f32_16x16x32_bf16 v[94:97], v[142:145], v[186:189], v[94:97]
	v_mfma_f32_16x16x32_bf16 v[90:93], v[134:137], v[190:193], v[90:93]
	v_mfma_f32_16x16x32_bf16 v[86:89], v[142:145], v[190:193], v[86:89]
	v_mfma_f32_16x16x32_bf16 v[82:85], v[146:149], v[162:165], v[82:85]
	v_mfma_f32_16x16x32_bf16 v[74:77], v[154:157], v[162:165], v[74:77]
	v_mfma_f32_16x16x32_bf16 v[70:73], v[146:149], v[166:169], v[70:73]
	v_mfma_f32_16x16x32_bf16 v[66:69], v[154:157], v[166:169], v[66:69]
	v_mfma_f32_16x16x32_bf16 v[62:65], v[146:149], v[178:181], v[62:65]
	v_mfma_f32_16x16x32_bf16 v[58:61], v[154:157], v[178:181], v[58:61]
	v_mfma_f32_16x16x32_bf16 v[54:57], v[146:149], v[182:185], v[54:57]
	v_mfma_f32_16x16x32_bf16 v[50:53], v[154:157], v[182:185], v[50:53]
	v_mfma_f32_16x16x32_bf16 v[82:85], v[150:153], v[170:173], v[82:85]
	v_mfma_f32_16x16x32_bf16 v[74:77], v[158:161], v[170:173], v[74:77]
	v_mfma_f32_16x16x32_bf16 v[70:73], v[150:153], v[174:177], v[70:73]
	v_mfma_f32_16x16x32_bf16 v[66:69], v[158:161], v[174:177], v[66:69]
	v_mfma_f32_16x16x32_bf16 v[62:65], v[150:153], v[186:189], v[62:65]
	v_mfma_f32_16x16x32_bf16 v[58:61], v[158:161], v[186:189], v[58:61]
	v_mfma_f32_16x16x32_bf16 v[54:57], v[150:153], v[190:193], v[54:57]
	v_mfma_f32_16x16x32_bf16 v[50:53], v[158:161], v[190:193], v[50:53]
	s_barrier
	s_setprio 0
	s_mov_b32 m0, s21
	ds_read_b128 v[162:165], v221 offset:16384
	ds_read_b128 v[166:169], v221 offset:18432
	ds_read_b128 v[170:173], v222 offset:16384
	ds_read_b128 v[174:177], v222 offset:18432
	ds_read_b128 v[178:181], v221 offset:20480
	ds_read_b128 v[182:185], v221 offset:22528
	ds_read_b128 v[186:189], v222 offset:20480
	ds_read_b128 v[190:193], v222 offset:22528
	buffer_load_dwordx4 v208, s[4:7], s60 offen lds
	s_mov_b32 m0, s22
	s_add_i32 s62, s60, 0x40000
	buffer_load_dwordx4 v210, s[4:7], s60 offen lds
	s_mov_b32 m0, s23
	s_nop 0
	buffer_load_dwordx4 v208, s[4:7], s62 offen lds
	s_mov_b32 m0, s24
	s_nop 0
	buffer_load_dwordx4 v210, s[4:7], s62 offen lds
	s_mov_b32 m0, s20
	s_nop 0
	buffer_load_dwordx4 v207, s[4:7], s61 offen lds
	s_mov_b32 m0, s25
	s_nop 0
	buffer_load_dwordx4 v209, s[4:7], s61 offen lds
	s_waitcnt vmcnt(8)
	s_waitcnt lgkmcnt(0)
	s_setprio 1
	s_barrier
	v_mfma_f32_16x16x32_bf16 v[78:81], v[130:133], v[162:165], v[78:81]
	v_mfma_f32_16x16x32_bf16 v[46:49], v[138:141], v[162:165], v[46:49]
	v_mfma_f32_16x16x32_bf16 v[42:45], v[130:133], v[166:169], v[42:45]
	v_mfma_f32_16x16x32_bf16 v[38:41], v[138:141], v[166:169], v[38:41]
	v_mfma_f32_16x16x32_bf16 v[34:37], v[130:133], v[178:181], v[34:37]
	v_mfma_f32_16x16x32_bf16 v[30:33], v[138:141], v[178:181], v[30:33]
	v_mfma_f32_16x16x32_bf16 v[26:29], v[130:133], v[182:185], v[26:29]
	v_mfma_f32_16x16x32_bf16 v[22:25], v[138:141], v[182:185], v[22:25]
	v_mfma_f32_16x16x32_bf16 v[78:81], v[134:137], v[170:173], v[78:81]
	v_mfma_f32_16x16x32_bf16 v[46:49], v[142:145], v[170:173], v[46:49]
	v_mfma_f32_16x16x32_bf16 v[42:45], v[134:137], v[174:177], v[42:45]
	v_mfma_f32_16x16x32_bf16 v[38:41], v[142:145], v[174:177], v[38:41]
	v_mfma_f32_16x16x32_bf16 v[34:37], v[134:137], v[186:189], v[34:37]
	v_mfma_f32_16x16x32_bf16 v[30:33], v[142:145], v[186:189], v[30:33]
	v_mfma_f32_16x16x32_bf16 v[26:29], v[134:137], v[190:193], v[26:29]
	v_mfma_f32_16x16x32_bf16 v[22:25], v[142:145], v[190:193], v[22:25]
	v_mfma_f32_16x16x32_bf16 v[18:21], v[146:149], v[162:165], v[18:21]
	v_mfma_f32_16x16x32_bf16 v[14:17], v[154:157], v[162:165], v[14:17]
	v_mfma_f32_16x16x32_bf16 v[10:13], v[146:149], v[166:169], v[10:13]
	v_mfma_f32_16x16x32_bf16 v[6:9], v[154:157], v[166:169], v[6:9]
	v_mfma_f32_16x16x32_bf16 v[2:5], v[146:149], v[178:181], v[2:5]
	v_mfma_f32_16x16x32_bf16 v[126:129], v[154:157], v[178:181], v[126:129]
	v_mfma_f32_16x16x32_bf16 v[122:125], v[146:149], v[182:185], v[122:125]
	v_mfma_f32_16x16x32_bf16 v[118:121], v[154:157], v[182:185], v[118:121]
	v_mfma_f32_16x16x32_bf16 v[18:21], v[150:153], v[170:173], v[18:21]
	v_mfma_f32_16x16x32_bf16 v[14:17], v[158:161], v[170:173], v[14:17]
	v_mfma_f32_16x16x32_bf16 v[10:13], v[150:153], v[174:177], v[10:13]
	v_mfma_f32_16x16x32_bf16 v[6:9], v[158:161], v[174:177], v[6:9]
	v_mfma_f32_16x16x32_bf16 v[2:5], v[150:153], v[186:189], v[2:5]
	v_mfma_f32_16x16x32_bf16 v[126:129], v[158:161], v[186:189], v[126:129]
	v_mfma_f32_16x16x32_bf16 v[122:125], v[150:153], v[190:193], v[122:125]
	v_mfma_f32_16x16x32_bf16 v[118:121], v[158:161], v[190:193], v[118:121]
	s_barrier
	s_setprio 0
	ds_read_b128 v[130:133], v194
	ds_read_b128 v[134:137], v224
	ds_read_b128 v[138:141], v225
	ds_read_b128 v[142:145], v228
	ds_read_b128 v[146:149], v229
	ds_read_b128 v[150:153], v230
	ds_read_b128 v[154:157], v231
	ds_read_b128 v[158:161], v233
	s_addk_i32 s61, 0x2000
	s_mov_b32 m0, s26
	ds_read_b128 v[162:165], v221 offset:32768
	ds_read_b128 v[166:169], v221 offset:34816
	ds_read_b128 v[170:173], v222 offset:32768
	ds_read_b128 v[174:177], v222 offset:34816
	ds_read_b128 v[178:181], v221 offset:36864
	ds_read_b128 v[182:185], v221 offset:38912
	ds_read_b128 v[186:189], v222 offset:36864
	ds_read_b128 v[190:193], v222 offset:38912
	buffer_load_dwordx4 v207, s[4:7], s61 offen lds
	s_mov_b32 m0, s27
	s_nop 0
	buffer_load_dwordx4 v209, s[4:7], s61 offen lds
	s_waitcnt vmcnt(8)
	s_waitcnt lgkmcnt(0)
	s_setprio 1
	v_mfma_f32_16x16x32_bf16 v[114:117], v[130:133], v[162:165], v[114:117]
	v_mfma_f32_16x16x32_bf16 v[110:113], v[138:141], v[162:165], v[110:113]
	v_mfma_f32_16x16x32_bf16 v[106:109], v[130:133], v[166:169], v[106:109]
	v_mfma_f32_16x16x32_bf16 v[102:105], v[138:141], v[166:169], v[102:105]
	s_barrier
	v_mfma_f32_16x16x32_bf16 v[98:101], v[130:133], v[178:181], v[98:101]
	v_mfma_f32_16x16x32_bf16 v[94:97], v[138:141], v[178:181], v[94:97]
	v_mfma_f32_16x16x32_bf16 v[90:93], v[130:133], v[182:185], v[90:93]
	v_mfma_f32_16x16x32_bf16 v[86:89], v[138:141], v[182:185], v[86:89]
	v_mfma_f32_16x16x32_bf16 v[114:117], v[134:137], v[170:173], v[114:117]
	v_mfma_f32_16x16x32_bf16 v[110:113], v[142:145], v[170:173], v[110:113]
	v_mfma_f32_16x16x32_bf16 v[106:109], v[134:137], v[174:177], v[106:109]
	v_mfma_f32_16x16x32_bf16 v[102:105], v[142:145], v[174:177], v[102:105]
	v_mfma_f32_16x16x32_bf16 v[98:101], v[134:137], v[186:189], v[98:101]
	v_mfma_f32_16x16x32_bf16 v[94:97], v[142:145], v[186:189], v[94:97]
	v_mfma_f32_16x16x32_bf16 v[90:93], v[134:137], v[190:193], v[90:93]
	v_mfma_f32_16x16x32_bf16 v[86:89], v[142:145], v[190:193], v[86:89]
	v_mfma_f32_16x16x32_bf16 v[82:85], v[146:149], v[162:165], v[82:85]
	v_mfma_f32_16x16x32_bf16 v[74:77], v[154:157], v[162:165], v[74:77]
	v_mfma_f32_16x16x32_bf16 v[70:73], v[146:149], v[166:169], v[70:73]
	v_mfma_f32_16x16x32_bf16 v[66:69], v[154:157], v[166:169], v[66:69]
	v_mfma_f32_16x16x32_bf16 v[62:65], v[146:149], v[178:181], v[62:65]
	v_mfma_f32_16x16x32_bf16 v[58:61], v[154:157], v[178:181], v[58:61]
	v_mfma_f32_16x16x32_bf16 v[54:57], v[146:149], v[182:185], v[54:57]
	v_mfma_f32_16x16x32_bf16 v[50:53], v[154:157], v[182:185], v[50:53]
	v_mfma_f32_16x16x32_bf16 v[82:85], v[150:153], v[170:173], v[82:85]
	v_mfma_f32_16x16x32_bf16 v[74:77], v[158:161], v[170:173], v[74:77]
	v_mfma_f32_16x16x32_bf16 v[70:73], v[150:153], v[174:177], v[70:73]
	v_mfma_f32_16x16x32_bf16 v[66:69], v[158:161], v[174:177], v[66:69]
	v_mfma_f32_16x16x32_bf16 v[62:65], v[150:153], v[186:189], v[62:65]
	v_mfma_f32_16x16x32_bf16 v[58:61], v[158:161], v[186:189], v[58:61]
	v_mfma_f32_16x16x32_bf16 v[54:57], v[150:153], v[190:193], v[54:57]
	v_mfma_f32_16x16x32_bf16 v[50:53], v[158:161], v[190:193], v[50:53]
	s_barrier
	s_setprio 0
	s_mov_b32 m0, s29
	s_add_i32 s61, s60, 0x80
	ds_read_b128 v[162:165], v221 offset:49152
	ds_read_b128 v[166:169], v221 offset:51200
	ds_read_b128 v[170:173], v222 offset:49152
	ds_read_b128 v[174:177], v222 offset:51200
	ds_read_b128 v[178:181], v221 offset:53248
	ds_read_b128 v[182:185], v221 offset:55296
	ds_read_b128 v[186:189], v222 offset:53248
	ds_read_b128 v[190:193], v222 offset:55296
	buffer_load_dwordx4 v208, s[4:7], s61 offen lds
	s_mov_b32 m0, s30
	s_add_i32 s60, s60, 0x40080
	buffer_load_dwordx4 v210, s[4:7], s61 offen lds
	s_mov_b32 m0, s35
	s_nop 0
	buffer_load_dwordx4 v208, s[4:7], s60 offen lds
	s_mov_b32 m0, s36
	s_nop 0
	buffer_load_dwordx4 v210, s[4:7], s60 offen lds
	s_mov_b32 m0, s31
	s_nop 0
	buffer_load_dwordx4 v207, s[4:7], s59 offen lds
	s_mov_b32 m0, s34
	s_nop 0
	buffer_load_dwordx4 v209, s[4:7], s59 offen lds
	s_waitcnt vmcnt(8)
	s_waitcnt lgkmcnt(0)
	s_setprio 1
	s_barrier
	v_mfma_f32_16x16x32_bf16 v[78:81], v[130:133], v[162:165], v[78:81]
	v_mfma_f32_16x16x32_bf16 v[46:49], v[138:141], v[162:165], v[46:49]
	v_mfma_f32_16x16x32_bf16 v[42:45], v[130:133], v[166:169], v[42:45]
	v_mfma_f32_16x16x32_bf16 v[38:41], v[138:141], v[166:169], v[38:41]
	v_mfma_f32_16x16x32_bf16 v[34:37], v[130:133], v[178:181], v[34:37]
	v_mfma_f32_16x16x32_bf16 v[30:33], v[138:141], v[178:181], v[30:33]
	v_mfma_f32_16x16x32_bf16 v[26:29], v[130:133], v[182:185], v[26:29]
	v_mfma_f32_16x16x32_bf16 v[22:25], v[138:141], v[182:185], v[22:25]
	v_mfma_f32_16x16x32_bf16 v[78:81], v[134:137], v[170:173], v[78:81]
	v_mfma_f32_16x16x32_bf16 v[46:49], v[142:145], v[170:173], v[46:49]
	v_mfma_f32_16x16x32_bf16 v[42:45], v[134:137], v[174:177], v[42:45]
	v_mfma_f32_16x16x32_bf16 v[38:41], v[142:145], v[174:177], v[38:41]
	v_mfma_f32_16x16x32_bf16 v[34:37], v[134:137], v[186:189], v[34:37]
	v_mfma_f32_16x16x32_bf16 v[30:33], v[142:145], v[186:189], v[30:33]
	v_mfma_f32_16x16x32_bf16 v[26:29], v[134:137], v[190:193], v[26:29]
	v_mfma_f32_16x16x32_bf16 v[22:25], v[142:145], v[190:193], v[22:25]
	v_mfma_f32_16x16x32_bf16 v[18:21], v[146:149], v[162:165], v[18:21]
	v_mfma_f32_16x16x32_bf16 v[14:17], v[154:157], v[162:165], v[14:17]
	v_mfma_f32_16x16x32_bf16 v[10:13], v[146:149], v[166:169], v[10:13]
	v_mfma_f32_16x16x32_bf16 v[6:9], v[154:157], v[166:169], v[6:9]
	v_mfma_f32_16x16x32_bf16 v[2:5], v[146:149], v[178:181], v[2:5]
	v_mfma_f32_16x16x32_bf16 v[126:129], v[154:157], v[178:181], v[126:129]
	v_mfma_f32_16x16x32_bf16 v[122:125], v[146:149], v[182:185], v[122:125]
	v_mfma_f32_16x16x32_bf16 v[118:121], v[154:157], v[182:185], v[118:121]
	v_mfma_f32_16x16x32_bf16 v[18:21], v[150:153], v[170:173], v[18:21]
	v_mfma_f32_16x16x32_bf16 v[14:17], v[158:161], v[170:173], v[14:17]
	v_mfma_f32_16x16x32_bf16 v[10:13], v[150:153], v[174:177], v[10:13]
	v_mfma_f32_16x16x32_bf16 v[6:9], v[158:161], v[174:177], v[6:9]
	v_mfma_f32_16x16x32_bf16 v[2:5], v[150:153], v[186:189], v[2:5]
	v_mfma_f32_16x16x32_bf16 v[126:129], v[158:161], v[186:189], v[126:129]
	v_mfma_f32_16x16x32_bf16 v[122:125], v[150:153], v[190:193], v[122:125]
	v_mfma_f32_16x16x32_bf16 v[118:121], v[158:161], v[190:193], v[118:121]
	s_barrier
	s_setprio 0
	s_add_i32 s58, s58, 2
	s_addk_i32 s33, 0x100
	s_addk_i32 s57, 0x100
	s_cmp_gt_u32 s58, 13
	s_cbranch_scc0 .LBB0_233
	s_and_b64 vcc, exec, s[16:17]
	s_cbranch_vccz .LBB0_236
	s_barrier

.LBB0_546:
	ds_read_b128 v[130:133], v211
	ds_read_b128 v[134:137], v212
	ds_read_b128 v[138:141], v213
	ds_read_b128 v[142:145], v214
	ds_read_b128 v[146:149], v215
	ds_read_b128 v[150:153], v216
	ds_read_b128 v[154:157], v217
	ds_read_b128 v[158:161], v218
	s_add_i32 s4, s62, 0x80
	s_cmp_eq_u32 s63, s78
	s_cselect_b32 s84, s64, s4
	s_cselect_b32 s82, s33, s59
	s_cselect_b32 s81, s65, s61
	s_cselect_b32 s80, s56, s60
	s_add_i32 s79, s84, 0x80
	s_add_i32 s83, s60, s62
	s_mov_b32 s4, s70
	s_mov_b32 m0, s43
	ds_read_b128 v[162:165], v219
	ds_read_b128 v[166:169], v219 offset:2048
	ds_read_b128 v[170:173], v220
	ds_read_b128 v[174:177], v220 offset:2048
	ds_read_b128 v[178:181], v219 offset:4096
	ds_read_b128 v[182:185], v219 offset:6144
	ds_read_b128 v[186:189], v220 offset:4096
	ds_read_b128 v[190:193], v220 offset:6144
	buffer_load_dwordx4 v194, s[4:7], s83 offen lds
	s_mov_b32 m0, s44
	s_nop 0
	buffer_load_dwordx4 v222, s[4:7], s83 offen lds
	s_waitcnt vmcnt(8)
	s_waitcnt lgkmcnt(0)
	s_setprio 1
	v_mfma_f32_16x16x32_bf16 v[126:129], v[130:133], v[162:165], v[126:129]
	v_mfma_f32_16x16x32_bf16 v[122:125], v[138:141], v[162:165], v[122:125]
	v_mfma_f32_16x16x32_bf16 v[118:121], v[130:133], v[166:169], v[118:121]
	v_mfma_f32_16x16x32_bf16 v[114:117], v[138:141], v[166:169], v[114:117]
	s_barrier
	v_mfma_f32_16x16x32_bf16 v[110:113], v[130:133], v[178:181], v[110:113]
	v_mfma_f32_16x16x32_bf16 v[106:109], v[138:141], v[178:181], v[106:109]
	v_mfma_f32_16x16x32_bf16 v[102:105], v[130:133], v[182:185], v[102:105]
	v_mfma_f32_16x16x32_bf16 v[98:101], v[138:141], v[182:185], v[98:101]
	v_mfma_f32_16x16x32_bf16 v[126:129], v[134:137], v[170:173], v[126:129]
	v_mfma_f32_16x16x32_bf16 v[122:125], v[142:145], v[170:173], v[122:125]
	v_mfma_f32_16x16x32_bf16 v[118:121], v[134:137], v[174:177], v[118:121]
	v_mfma_f32_16x16x32_bf16 v[114:117], v[142:145], v[174:177], v[114:117]
	v_mfma_f32_16x16x32_bf16 v[110:113], v[134:137], v[186:189], v[110:113]
	v_mfma_f32_16x16x32_bf16 v[106:109], v[142:145], v[186:189], v[106:109]
	v_mfma_f32_16x16x32_bf16 v[102:105], v[134:137], v[190:193], v[102:105]
	v_mfma_f32_16x16x32_bf16 v[98:101], v[142:145], v[190:193], v[98:101]
	v_mfma_f32_16x16x32_bf16 v[94:97], v[146:149], v[162:165], v[94:97]
	v_mfma_f32_16x16x32_bf16 v[90:93], v[154:157], v[162:165], v[90:93]
	v_mfma_f32_16x16x32_bf16 v[86:89], v[146:149], v[166:169], v[86:89]
	v_mfma_f32_16x16x32_bf16 v[82:85], v[154:157], v[166:169], v[82:85]
	v_mfma_f32_16x16x32_bf16 v[78:81], v[146:149], v[178:181], v[78:81]
	v_mfma_f32_16x16x32_bf16 v[74:77], v[154:157], v[178:181], v[74:77]
	v_mfma_f32_16x16x32_bf16 v[70:73], v[146:149], v[182:185], v[70:73]
	v_mfma_f32_16x16x32_bf16 v[66:69], v[154:157], v[182:185], v[66:69]
	v_mfma_f32_16x16x32_bf16 v[94:97], v[150:153], v[170:173], v[94:97]
	v_mfma_f32_16x16x32_bf16 v[90:93], v[158:161], v[170:173], v[90:93]
	v_mfma_f32_16x16x32_bf16 v[86:89], v[150:153], v[174:177], v[86:89]
	v_mfma_f32_16x16x32_bf16 v[82:85], v[158:161], v[174:177], v[82:85]
	v_mfma_f32_16x16x32_bf16 v[78:81], v[150:153], v[186:189], v[78:81]
	v_mfma_f32_16x16x32_bf16 v[74:77], v[158:161], v[186:189], v[74:77]
	v_mfma_f32_16x16x32_bf16 v[70:73], v[150:153], v[190:193], v[70:73]
	v_mfma_f32_16x16x32_bf16 v[66:69], v[158:161], v[190:193], v[66:69]
	s_barrier
	s_setprio 0
	s_cmp_eq_u32 s82, 0
	s_cselect_b64 s[82:83], -1, 0
	v_cndmask_b32_e64 v233, v200, 0, s[82:83]
	s_mov_b32 m0, s25
	v_sub_u32_e32 v233, v201, v233
	v_cndmask_b32_e64 v234, v203, 0, s[82:83]
	ds_read_b128 v[162:165], v219 offset:16384
	ds_read_b128 v[166:169], v219 offset:18432
	ds_read_b128 v[170:173], v220 offset:16384
	ds_read_b128 v[174:177], v220 offset:18432
	ds_read_b128 v[178:181], v219 offset:20480
	ds_read_b128 v[182:185], v219 offset:22528
	ds_read_b128 v[186:189], v220 offset:20480
	ds_read_b128 v[190:193], v220 offset:22528
	buffer_load_dwordx4 v233, s[4:7], s81 offen lds
	v_sub_u32_e32 v234, v204, v234
	s_mov_b32 m0, s26
	s_add_i32 s85, s81, s80
	buffer_load_dwordx4 v234, s[4:7], s81 offen lds
	s_mov_b32 m0, s27
	v_cndmask_b32_e64 v235, v205, 0, s[82:83]
	buffer_load_dwordx4 v233, s[4:7], s85 offen lds
	s_mov_b32 m0, s28
	v_sub_u32_e32 v235, v1, v235
	buffer_load_dwordx4 v234, s[4:7], s85 offen lds
	s_mov_b32 m0, s24
	v_cndmask_b32_e64 v236, v206, 0, s[82:83]
	buffer_load_dwordx4 v235, s[4:7], s84 offen lds
	v_sub_u32_e32 v236, v202, v236
	s_mov_b32 m0, s29
	s_nop 0
	buffer_load_dwordx4 v236, s[4:7], s84 offen lds
	s_waitcnt vmcnt(8)
	s_waitcnt lgkmcnt(0)
	s_setprio 1
	s_barrier
	v_mfma_f32_16x16x32_bf16 v[62:65], v[130:133], v[162:165], v[62:65]
	v_mfma_f32_16x16x32_bf16 v[58:61], v[138:141], v[162:165], v[58:61]
	v_mfma_f32_16x16x32_bf16 v[54:57], v[130:133], v[166:169], v[54:57]
	v_mfma_f32_16x16x32_bf16 v[50:53], v[138:141], v[166:169], v[50:53]
	v_mfma_f32_16x16x32_bf16 v[46:49], v[130:133], v[178:181], v[46:49]
	v_mfma_f32_16x16x32_bf16 v[42:45], v[138:141], v[178:181], v[42:45]
	v_mfma_f32_16x16x32_bf16 v[38:41], v[130:133], v[182:185], v[38:41]
	v_mfma_f32_16x16x32_bf16 v[34:37], v[138:141], v[182:185], v[34:37]
	v_mfma_f32_16x16x32_bf16 v[62:65], v[134:137], v[170:173], v[62:65]
	v_mfma_f32_16x16x32_bf16 v[58:61], v[142:145], v[170:173], v[58:61]
	v_mfma_f32_16x16x32_bf16 v[54:57], v[134:137], v[174:177], v[54:57]
	v_mfma_f32_16x16x32_bf16 v[50:53], v[142:145], v[174:177], v[50:53]
	v_mfma_f32_16x16x32_bf16 v[46:49], v[134:137], v[186:189], v[46:49]
	v_mfma_f32_16x16x32_bf16 v[42:45], v[142:145], v[186:189], v[42:45]
	v_mfma_f32_16x16x32_bf16 v[38:41], v[134:137], v[190:193], v[38:41]
	v_mfma_f32_16x16x32_bf16 v[34:37], v[142:145], v[190:193], v[34:37]
	v_mfma_f32_16x16x32_bf16 v[30:33], v[146:149], v[162:165], v[30:33]
	v_mfma_f32_16x16x32_bf16 v[26:29], v[154:157], v[162:165], v[26:29]
	v_mfma_f32_16x16x32_bf16 v[22:25], v[146:149], v[166:169], v[22:25]
	v_mfma_f32_16x16x32_bf16 v[18:21], v[154:157], v[166:169], v[18:21]
	v_mfma_f32_16x16x32_bf16 v[14:17], v[146:149], v[178:181], v[14:17]
	v_mfma_f32_16x16x32_bf16 v[10:13], v[154:157], v[178:181], v[10:13]
	v_mfma_f32_16x16x32_bf16 v[6:9], v[146:149], v[182:185], v[6:9]
	v_mfma_f32_16x16x32_bf16 v[2:5], v[154:157], v[182:185], v[2:5]
	v_mfma_f32_16x16x32_bf16 v[30:33], v[150:153], v[170:173], v[30:33]
	v_mfma_f32_16x16x32_bf16 v[26:29], v[158:161], v[170:173], v[26:29]
	v_mfma_f32_16x16x32_bf16 v[22:25], v[150:153], v[174:177], v[22:25]
	v_mfma_f32_16x16x32_bf16 v[18:21], v[158:161], v[174:177], v[18:21]
	v_mfma_f32_16x16x32_bf16 v[14:17], v[150:153], v[186:189], v[14:17]
	v_mfma_f32_16x16x32_bf16 v[10:13], v[158:161], v[186:189], v[10:13]
	v_mfma_f32_16x16x32_bf16 v[6:9], v[150:153], v[190:193], v[6:9]
	v_mfma_f32_16x16x32_bf16 v[2:5], v[158:161], v[190:193], v[2:5]
	s_barrier
	s_setprio 0
	ds_read_b128 v[130:133], v223
	ds_read_b128 v[134:137], v224
	ds_read_b128 v[138:141], v225
	ds_read_b128 v[142:145], v227
	ds_read_b128 v[146:149], v228
	ds_read_b128 v[150:153], v229
	ds_read_b128 v[154:157], v230
	ds_read_b128 v[158:161], v231
	s_add_i32 s84, s84, s80
	s_mov_b32 m0, s30
	ds_read_b128 v[162:165], v219 offset:32768
	ds_read_b128 v[166:169], v219 offset:34816
	ds_read_b128 v[170:173], v220 offset:32768
	ds_read_b128 v[174:177], v220 offset:34816
	ds_read_b128 v[178:181], v219 offset:36864
	ds_read_b128 v[182:185], v219 offset:38912
	ds_read_b128 v[186:189], v220 offset:36864
	ds_read_b128 v[190:193], v220 offset:38912
	buffer_load_dwordx4 v235, s[4:7], s84 offen lds
	s_mov_b32 m0, s31
	s_nop 0
	buffer_load_dwordx4 v236, s[4:7], s84 offen lds
	s_waitcnt vmcnt(8)
	s_waitcnt lgkmcnt(0)
	s_setprio 1
	v_mfma_f32_16x16x32_bf16 v[126:129], v[130:133], v[162:165], v[126:129]
	v_mfma_f32_16x16x32_bf16 v[122:125], v[138:141], v[162:165], v[122:125]
	v_mfma_f32_16x16x32_bf16 v[118:121], v[130:133], v[166:169], v[118:121]
	v_mfma_f32_16x16x32_bf16 v[114:117], v[138:141], v[166:169], v[114:117]
	s_barrier
	v_mfma_f32_16x16x32_bf16 v[110:113], v[130:133], v[178:181], v[110:113]
	v_mfma_f32_16x16x32_bf16 v[106:109], v[138:141], v[178:181], v[106:109]
	v_mfma_f32_16x16x32_bf16 v[102:105], v[130:133], v[182:185], v[102:105]
	v_mfma_f32_16x16x32_bf16 v[98:101], v[138:141], v[182:185], v[98:101]
	v_mfma_f32_16x16x32_bf16 v[126:129], v[134:137], v[170:173], v[126:129]
	v_mfma_f32_16x16x32_bf16 v[122:125], v[142:145], v[170:173], v[122:125]
	v_mfma_f32_16x16x32_bf16 v[118:121], v[134:137], v[174:177], v[118:121]
	v_mfma_f32_16x16x32_bf16 v[114:117], v[142:145], v[174:177], v[114:117]
	v_mfma_f32_16x16x32_bf16 v[110:113], v[134:137], v[186:189], v[110:113]
	v_mfma_f32_16x16x32_bf16 v[106:109], v[142:145], v[186:189], v[106:109]
	v_mfma_f32_16x16x32_bf16 v[102:105], v[134:137], v[190:193], v[102:105]
	v_mfma_f32_16x16x32_bf16 v[98:101], v[142:145], v[190:193], v[98:101]
	v_mfma_f32_16x16x32_bf16 v[94:97], v[146:149], v[162:165], v[94:97]
	v_mfma_f32_16x16x32_bf16 v[90:93], v[154:157], v[162:165], v[90:93]
	v_mfma_f32_16x16x32_bf16 v[86:89], v[146:149], v[166:169], v[86:89]
	v_mfma_f32_16x16x32_bf16 v[82:85], v[154:157], v[166:169], v[82:85]
	v_mfma_f32_16x16x32_bf16 v[78:81], v[146:149], v[178:181], v[78:81]
	v_mfma_f32_16x16x32_bf16 v[74:77], v[154:157], v[178:181], v[74:77]
	v_mfma_f32_16x16x32_bf16 v[70:73], v[146:149], v[182:185], v[70:73]
	v_mfma_f32_16x16x32_bf16 v[66:69], v[154:157], v[182:185], v[66:69]
	v_mfma_f32_16x16x32_bf16 v[94:97], v[150:153], v[170:173], v[94:97]
	v_mfma_f32_16x16x32_bf16 v[90:93], v[158:161], v[170:173], v[90:93]
	v_mfma_f32_16x16x32_bf16 v[86:89], v[150:153], v[174:177], v[86:89]
	v_mfma_f32_16x16x32_bf16 v[82:85], v[158:161], v[174:177], v[82:85]
	v_mfma_f32_16x16x32_bf16 v[78:81], v[150:153], v[186:189], v[78:81]
	v_mfma_f32_16x16x32_bf16 v[74:77], v[158:161], v[186:189], v[74:77]
	v_mfma_f32_16x16x32_bf16 v[70:73], v[150:153], v[190:193], v[70:73]
	v_mfma_f32_16x16x32_bf16 v[66:69], v[158:161], v[190:193], v[66:69]
	s_barrier
	s_setprio 0
	s_mov_b32 m0, s36
	s_addk_i32 s81, 0x80
	ds_read_b128 v[162:165], v219 offset:49152
	ds_read_b128 v[166:169], v219 offset:51200
	ds_read_b128 v[170:173], v220 offset:49152
	ds_read_b128 v[174:177], v220 offset:51200
	ds_read_b128 v[178:181], v219 offset:53248
	ds_read_b128 v[182:185], v219 offset:55296
	ds_read_b128 v[186:189], v220 offset:53248
	ds_read_b128 v[190:193], v220 offset:55296
	buffer_load_dwordx4 v233, s[4:7], s81 offen lds
	s_mov_b32 m0, s37
	s_nop 0
	buffer_load_dwordx4 v234, s[4:7], s81 offen lds
	s_add_i32 s81, s81, s80
	s_mov_b32 m0, s40
	s_nop 0
	buffer_load_dwordx4 v233, s[4:7], s81 offen lds
	s_mov_b32 m0, s41
	s_nop 0
	buffer_load_dwordx4 v234, s[4:7], s81 offen lds
	s_mov_b32 m0, s38
	s_nop 0
	buffer_load_dwordx4 v235, s[4:7], s79 offen lds
	s_mov_b32 m0, s39
	s_nop 0
	buffer_load_dwordx4 v236, s[4:7], s79 offen lds
	s_waitcnt vmcnt(8)
	s_waitcnt lgkmcnt(0)
	s_setprio 1
	s_barrier
	v_mfma_f32_16x16x32_bf16 v[62:65], v[130:133], v[162:165], v[62:65]
	v_mfma_f32_16x16x32_bf16 v[58:61], v[138:141], v[162:165], v[58:61]
	v_mfma_f32_16x16x32_bf16 v[54:57], v[130:133], v[166:169], v[54:57]
	v_mfma_f32_16x16x32_bf16 v[50:53], v[138:141], v[166:169], v[50:53]
	v_mfma_f32_16x16x32_bf16 v[46:49], v[130:133], v[178:181], v[46:49]
	v_mfma_f32_16x16x32_bf16 v[42:45], v[138:141], v[178:181], v[42:45]
	v_mfma_f32_16x16x32_bf16 v[38:41], v[130:133], v[182:185], v[38:41]
	v_mfma_f32_16x16x32_bf16 v[34:37], v[138:141], v[182:185], v[34:37]
	v_mfma_f32_16x16x32_bf16 v[62:65], v[134:137], v[170:173], v[62:65]
	v_mfma_f32_16x16x32_bf16 v[58:61], v[142:145], v[170:173], v[58:61]
	v_mfma_f32_16x16x32_bf16 v[54:57], v[134:137], v[174:177], v[54:57]
	v_mfma_f32_16x16x32_bf16 v[50:53], v[142:145], v[174:177], v[50:53]
	v_mfma_f32_16x16x32_bf16 v[46:49], v[134:137], v[186:189], v[46:49]
	v_mfma_f32_16x16x32_bf16 v[42:45], v[142:145], v[186:189], v[42:45]
	v_mfma_f32_16x16x32_bf16 v[38:41], v[134:137], v[190:193], v[38:41]
	v_mfma_f32_16x16x32_bf16 v[34:37], v[142:145], v[190:193], v[34:37]
	v_mfma_f32_16x16x32_bf16 v[30:33], v[146:149], v[162:165], v[30:33]
	v_mfma_f32_16x16x32_bf16 v[26:29], v[154:157], v[162:165], v[26:29]
	v_mfma_f32_16x16x32_bf16 v[22:25], v[146:149], v[166:169], v[22:25]
	v_mfma_f32_16x16x32_bf16 v[18:21], v[154:157], v[166:169], v[18:21]
	v_mfma_f32_16x16x32_bf16 v[14:17], v[146:149], v[178:181], v[14:17]
	v_mfma_f32_16x16x32_bf16 v[10:13], v[154:157], v[178:181], v[10:13]
	v_mfma_f32_16x16x32_bf16 v[6:9], v[146:149], v[182:185], v[6:9]
	v_mfma_f32_16x16x32_bf16 v[2:5], v[154:157], v[182:185], v[2:5]
	v_mfma_f32_16x16x32_bf16 v[30:33], v[150:153], v[170:173], v[30:33]
	v_mfma_f32_16x16x32_bf16 v[26:29], v[158:161], v[170:173], v[26:29]
	v_mfma_f32_16x16x32_bf16 v[22:25], v[150:153], v[174:177], v[22:25]
	v_mfma_f32_16x16x32_bf16 v[18:21], v[158:161], v[174:177], v[18:21]
	v_mfma_f32_16x16x32_bf16 v[14:17], v[150:153], v[186:189], v[14:17]
	v_mfma_f32_16x16x32_bf16 v[10:13], v[158:161], v[186:189], v[10:13]
	v_mfma_f32_16x16x32_bf16 v[6:9], v[150:153], v[190:193], v[6:9]
	v_mfma_f32_16x16x32_bf16 v[2:5], v[158:161], v[190:193], v[2:5]
	s_barrier
	s_setprio 0
	s_add_i32 s4, s78, 2
	s_addk_i32 s62, 0x100
	s_addk_i32 s61, 0x100
	s_cmp_ge_u32 s78, s63
	s_mov_b32 s78, s4
	s_cbranch_scc0 .LBB0_546
	s_and_b64 vcc, exec, s[12:13]
	s_cbranch_vccz .LBB0_549
	s_barrier

.LBB0_841:
	ds_read_b128 v[130:133], v240
	ds_read_b128 v[134:137], v241
	ds_read_b128 v[138:141], v242
	ds_read_b128 v[142:145], v243
	ds_read_b128 v[146:149], v244
	ds_read_b128 v[150:153], v245
	ds_read_b128 v[154:157], v246
	ds_read_b128 v[158:161], v247
	s_add_i32 s8, s42, s5
	s_add_i32 s19, s34, s5
	s_add_i32 s18, s8, 0x800
	s_addk_i32 s19, 0x800
	s_cmp_eq_u32 s5, 0
	s_cselect_b32 s20, s0, s18
	s_cselect_b32 s19, s1, s19
	s_add_i32 s18, s20, 0x80
	s_add_i32 s21, s8, 0x40780
	s_mov_b32 s8, s70
	s_mov_b32 m0, s52
	ds_read_b128 v[162:165], v248
	ds_read_b128 v[166:169], v248 offset:2048
	ds_read_b128 v[170:173], v249
	ds_read_b128 v[174:177], v249 offset:2048
	ds_read_b128 v[178:181], v248 offset:4096
	ds_read_b128 v[182:185], v248 offset:6144
	ds_read_b128 v[186:189], v249 offset:4096
	ds_read_b128 v[190:193], v249 offset:6144
	buffer_load_dwordx4 v1, s[8:11], s21 offen lds
	s_mov_b32 m0, s53
	s_nop 0
	buffer_load_dwordx4 v234, s[8:11], s21 offen lds
	s_waitcnt vmcnt(8)
	s_waitcnt lgkmcnt(0)
	s_setprio 1
	v_mfma_f32_16x16x32_bf16 v[74:77], v[130:133], v[162:165], v[74:77]
	v_mfma_f32_16x16x32_bf16 v[70:73], v[138:141], v[162:165], v[70:73]
	v_mfma_f32_16x16x32_bf16 v[66:69], v[130:133], v[166:169], v[66:69]
	v_mfma_f32_16x16x32_bf16 v[82:85], v[138:141], v[166:169], v[82:85]
	s_barrier
	v_mfma_f32_16x16x32_bf16 v[78:81], v[130:133], v[178:181], v[78:81]
	v_mfma_f32_16x16x32_bf16 v[90:93], v[138:141], v[178:181], v[90:93]
	v_mfma_f32_16x16x32_bf16 v[86:89], v[130:133], v[182:185], v[86:89]
	v_mfma_f32_16x16x32_bf16 v[102:105], v[138:141], v[182:185], v[102:105]
	v_mfma_f32_16x16x32_bf16 v[74:77], v[134:137], v[170:173], v[74:77]
	v_mfma_f32_16x16x32_bf16 v[70:73], v[142:145], v[170:173], v[70:73]
	v_mfma_f32_16x16x32_bf16 v[66:69], v[134:137], v[174:177], v[66:69]
	v_mfma_f32_16x16x32_bf16 v[82:85], v[142:145], v[174:177], v[82:85]
	v_mfma_f32_16x16x32_bf16 v[78:81], v[134:137], v[186:189], v[78:81]
	v_mfma_f32_16x16x32_bf16 v[90:93], v[142:145], v[186:189], v[90:93]
	v_mfma_f32_16x16x32_bf16 v[86:89], v[134:137], v[190:193], v[86:89]
	v_mfma_f32_16x16x32_bf16 v[102:105], v[142:145], v[190:193], v[102:105]
	v_mfma_f32_16x16x32_bf16 v[98:101], v[146:149], v[162:165], v[98:101]
	v_mfma_f32_16x16x32_bf16 v[94:97], v[154:157], v[162:165], v[94:97]
	v_mfma_f32_16x16x32_bf16 v[106:109], v[146:149], v[166:169], v[106:109]
	v_mfma_f32_16x16x32_bf16 v[110:113], v[154:157], v[166:169], v[110:113]
	v_mfma_f32_16x16x32_bf16 v[114:117], v[146:149], v[178:181], v[114:117]
	v_mfma_f32_16x16x32_bf16 v[118:121], v[154:157], v[178:181], v[118:121]
	v_mfma_f32_16x16x32_bf16 v[122:125], v[146:149], v[182:185], v[122:125]
	v_mfma_f32_16x16x32_bf16 v[126:129], v[154:157], v[182:185], v[126:129]
	v_mfma_f32_16x16x32_bf16 v[98:101], v[150:153], v[170:173], v[98:101]
	v_mfma_f32_16x16x32_bf16 v[94:97], v[158:161], v[170:173], v[94:97]
	v_mfma_f32_16x16x32_bf16 v[106:109], v[150:153], v[174:177], v[106:109]
	v_mfma_f32_16x16x32_bf16 v[110:113], v[158:161], v[174:177], v[110:113]
	v_mfma_f32_16x16x32_bf16 v[114:117], v[150:153], v[186:189], v[114:117]
	v_mfma_f32_16x16x32_bf16 v[118:121], v[158:161], v[186:189], v[118:121]
	v_mfma_f32_16x16x32_bf16 v[122:125], v[150:153], v[190:193], v[122:125]
	v_mfma_f32_16x16x32_bf16 v[126:129], v[158:161], v[190:193], v[126:129]
	s_barrier
	s_setprio 0
	s_mov_b32 m0, s29
	ds_read_b128 v[162:165], v248 offset:16384
	ds_read_b128 v[166:169], v248 offset:18432
	ds_read_b128 v[170:173], v249 offset:16384
	ds_read_b128 v[174:177], v249 offset:18432
	ds_read_b128 v[178:181], v248 offset:20480
	ds_read_b128 v[182:185], v248 offset:22528
	ds_read_b128 v[186:189], v249 offset:20480
	ds_read_b128 v[190:193], v249 offset:22528
	buffer_load_dwordx4 v233, s[8:11], s19 offen lds
	s_mov_b32 m0, s30
	s_add_i32 s21, s19, 0x40000
	buffer_load_dwordx4 v235, s[8:11], s19 offen lds
	s_mov_b32 m0, s31
	s_nop 0
	buffer_load_dwordx4 v233, s[8:11], s21 offen lds
	s_mov_b32 m0, s35
	s_nop 0
	buffer_load_dwordx4 v235, s[8:11], s21 offen lds
	s_mov_b32 m0, s28
	s_nop 0
	buffer_load_dwordx4 v1, s[8:11], s20 offen lds
	s_mov_b32 m0, s38
	s_nop 0
	buffer_load_dwordx4 v234, s[8:11], s20 offen lds
	s_waitcnt vmcnt(8)
	s_waitcnt lgkmcnt(0)
	s_setprio 1
	s_barrier
	v_mfma_f32_16x16x32_bf16 v[10:13], v[130:133], v[162:165], v[10:13]
	v_mfma_f32_16x16x32_bf16 v[6:9], v[138:141], v[162:165], v[6:9]
	v_mfma_f32_16x16x32_bf16 v[2:5], v[130:133], v[166:169], v[2:5]
	v_mfma_f32_16x16x32_bf16 v[18:21], v[138:141], v[166:169], v[18:21]
	v_mfma_f32_16x16x32_bf16 v[14:17], v[130:133], v[178:181], v[14:17]
	v_mfma_f32_16x16x32_bf16 v[26:29], v[138:141], v[178:181], v[26:29]
	v_mfma_f32_16x16x32_bf16 v[22:25], v[130:133], v[182:185], v[22:25]
	v_mfma_f32_16x16x32_bf16 v[38:41], v[138:141], v[182:185], v[38:41]
	v_mfma_f32_16x16x32_bf16 v[10:13], v[134:137], v[170:173], v[10:13]
	v_mfma_f32_16x16x32_bf16 v[6:9], v[142:145], v[170:173], v[6:9]
	v_mfma_f32_16x16x32_bf16 v[2:5], v[134:137], v[174:177], v[2:5]
	v_mfma_f32_16x16x32_bf16 v[18:21], v[142:145], v[174:177], v[18:21]
	v_mfma_f32_16x16x32_bf16 v[14:17], v[134:137], v[186:189], v[14:17]
	v_mfma_f32_16x16x32_bf16 v[26:29], v[142:145], v[186:189], v[26:29]
	v_mfma_f32_16x16x32_bf16 v[22:25], v[134:137], v[190:193], v[22:25]
	v_mfma_f32_16x16x32_bf16 v[38:41], v[142:145], v[190:193], v[38:41]
	v_mfma_f32_16x16x32_bf16 v[34:37], v[146:149], v[162:165], v[34:37]
	v_mfma_f32_16x16x32_bf16 v[30:33], v[154:157], v[162:165], v[30:33]
	v_mfma_f32_16x16x32_bf16 v[42:45], v[146:149], v[166:169], v[42:45]
	v_mfma_f32_16x16x32_bf16 v[46:49], v[154:157], v[166:169], v[46:49]
	v_mfma_f32_16x16x32_bf16 v[50:53], v[146:149], v[178:181], v[50:53]
	v_mfma_f32_16x16x32_bf16 v[54:57], v[154:157], v[178:181], v[54:57]
	v_mfma_f32_16x16x32_bf16 v[58:61], v[146:149], v[182:185], v[58:61]
	v_mfma_f32_16x16x32_bf16 v[62:65], v[154:157], v[182:185], v[62:65]
	v_mfma_f32_16x16x32_bf16 v[34:37], v[150:153], v[170:173], v[34:37]
	v_mfma_f32_16x16x32_bf16 v[30:33], v[158:161], v[170:173], v[30:33]
	v_mfma_f32_16x16x32_bf16 v[42:45], v[150:153], v[174:177], v[42:45]
	v_mfma_f32_16x16x32_bf16 v[46:49], v[158:161], v[174:177], v[46:49]
	v_mfma_f32_16x16x32_bf16 v[50:53], v[150:153], v[186:189], v[50:53]
	v_mfma_f32_16x16x32_bf16 v[54:57], v[158:161], v[186:189], v[54:57]
	v_mfma_f32_16x16x32_bf16 v[58:61], v[150:153], v[190:193], v[58:61]
	v_mfma_f32_16x16x32_bf16 v[62:65], v[158:161], v[190:193], v[62:65]
	s_barrier
	s_setprio 0
	ds_read_b128 v[130:133], v194
	ds_read_b128 v[134:137], v195
	ds_read_b128 v[138:141], v196
	ds_read_b128 v[142:145], v197
	ds_read_b128 v[146:149], v198
	ds_read_b128 v[150:153], v199
	ds_read_b128 v[154:157], v200
	ds_read_b128 v[158:161], v201
	s_add_i32 s20, s20, 0x40000
	s_mov_b32 m0, s39
	ds_read_b128 v[162:165], v248 offset:32768
	ds_read_b128 v[166:169], v248 offset:34816
	ds_read_b128 v[170:173], v249 offset:32768
	ds_read_b128 v[174:177], v249 offset:34816
	ds_read_b128 v[178:181], v248 offset:36864
	ds_read_b128 v[182:185], v248 offset:38912
	ds_read_b128 v[186:189], v249 offset:36864
	ds_read_b128 v[190:193], v249 offset:38912
	buffer_load_dwordx4 v1, s[8:11], s20 offen lds
	s_mov_b32 m0, s41
	s_nop 0
	buffer_load_dwordx4 v234, s[8:11], s20 offen lds
	s_waitcnt vmcnt(8)
	s_waitcnt lgkmcnt(0)
	s_setprio 1
	v_mfma_f32_16x16x32_bf16 v[74:77], v[130:133], v[162:165], v[74:77]
	v_mfma_f32_16x16x32_bf16 v[70:73], v[138:141], v[162:165], v[70:73]
	v_mfma_f32_16x16x32_bf16 v[66:69], v[130:133], v[166:169], v[66:69]
	v_mfma_f32_16x16x32_bf16 v[82:85], v[138:141], v[166:169], v[82:85]
	s_barrier
	v_mfma_f32_16x16x32_bf16 v[78:81], v[130:133], v[178:181], v[78:81]
	v_mfma_f32_16x16x32_bf16 v[90:93], v[138:141], v[178:181], v[90:93]
	v_mfma_f32_16x16x32_bf16 v[86:89], v[130:133], v[182:185], v[86:89]
	v_mfma_f32_16x16x32_bf16 v[102:105], v[138:141], v[182:185], v[102:105]
	v_mfma_f32_16x16x32_bf16 v[74:77], v[134:137], v[170:173], v[74:77]
	v_mfma_f32_16x16x32_bf16 v[70:73], v[142:145], v[170:173], v[70:73]
	v_mfma_f32_16x16x32_bf16 v[66:69], v[134:137], v[174:177], v[66:69]
	v_mfma_f32_16x16x32_bf16 v[82:85], v[142:145], v[174:177], v[82:85]
	v_mfma_f32_16x16x32_bf16 v[78:81], v[134:137], v[186:189], v[78:81]
	v_mfma_f32_16x16x32_bf16 v[90:93], v[142:145], v[186:189], v[90:93]
	v_mfma_f32_16x16x32_bf16 v[86:89], v[134:137], v[190:193], v[86:89]
	v_mfma_f32_16x16x32_bf16 v[102:105], v[142:145], v[190:193], v[102:105]
	v_mfma_f32_16x16x32_bf16 v[98:101], v[146:149], v[162:165], v[98:101]
	v_mfma_f32_16x16x32_bf16 v[94:97], v[154:157], v[162:165], v[94:97]
	v_mfma_f32_16x16x32_bf16 v[106:109], v[146:149], v[166:169], v[106:109]
	v_mfma_f32_16x16x32_bf16 v[110:113], v[154:157], v[166:169], v[110:113]
	v_mfma_f32_16x16x32_bf16 v[114:117], v[146:149], v[178:181], v[114:117]
	v_mfma_f32_16x16x32_bf16 v[118:121], v[154:157], v[178:181], v[118:121]
	v_mfma_f32_16x16x32_bf16 v[122:125], v[146:149], v[182:185], v[122:125]
	v_mfma_f32_16x16x32_bf16 v[126:129], v[154:157], v[182:185], v[126:129]
	v_mfma_f32_16x16x32_bf16 v[98:101], v[150:153], v[170:173], v[98:101]
	v_mfma_f32_16x16x32_bf16 v[94:97], v[158:161], v[170:173], v[94:97]
	v_mfma_f32_16x16x32_bf16 v[106:109], v[150:153], v[174:177], v[106:109]
	v_mfma_f32_16x16x32_bf16 v[110:113], v[158:161], v[174:177], v[110:113]
	v_mfma_f32_16x16x32_bf16 v[114:117], v[150:153], v[186:189], v[114:117]
	v_mfma_f32_16x16x32_bf16 v[118:121], v[158:161], v[186:189], v[118:121]
	v_mfma_f32_16x16x32_bf16 v[122:125], v[150:153], v[190:193], v[122:125]
	v_mfma_f32_16x16x32_bf16 v[126:129], v[158:161], v[190:193], v[126:129]
	s_barrier
	s_setprio 0
	s_mov_b32 m0, s44
	s_add_i32 s20, s19, 0x80
	ds_read_b128 v[162:165], v248 offset:49152
	ds_read_b128 v[166:169], v248 offset:51200
	ds_read_b128 v[170:173], v249 offset:49152
	ds_read_b128 v[174:177], v249 offset:51200
	ds_read_b128 v[178:181], v248 offset:53248
	ds_read_b128 v[182:185], v248 offset:55296
	ds_read_b128 v[186:189], v249 offset:53248
	ds_read_b128 v[190:193], v249 offset:55296
	buffer_load_dwordx4 v233, s[8:11], s20 offen lds
	s_mov_b32 m0, s45
	s_add_i32 s19, s19, 0x40080
	buffer_load_dwordx4 v235, s[8:11], s20 offen lds
	s_mov_b32 m0, s48
	s_nop 0
	buffer_load_dwordx4 v233, s[8:11], s19 offen lds
	s_mov_b32 m0, s49
	s_nop 0
	buffer_load_dwordx4 v235, s[8:11], s19 offen lds
	s_mov_b32 m0, s46
	s_nop 0
	buffer_load_dwordx4 v1, s[8:11], s18 offen lds
	s_mov_b32 m0, s47
	s_nop 0
	buffer_load_dwordx4 v234, s[8:11], s18 offen lds
	s_waitcnt vmcnt(8)
	s_waitcnt lgkmcnt(0)
	s_setprio 1
	s_barrier
	v_mfma_f32_16x16x32_bf16 v[10:13], v[130:133], v[162:165], v[10:13]
	v_mfma_f32_16x16x32_bf16 v[6:9], v[138:141], v[162:165], v[6:9]
	v_mfma_f32_16x16x32_bf16 v[2:5], v[130:133], v[166:169], v[2:5]
	v_mfma_f32_16x16x32_bf16 v[18:21], v[138:141], v[166:169], v[18:21]
	v_mfma_f32_16x16x32_bf16 v[14:17], v[130:133], v[178:181], v[14:17]
	v_mfma_f32_16x16x32_bf16 v[26:29], v[138:141], v[178:181], v[26:29]
	v_mfma_f32_16x16x32_bf16 v[22:25], v[130:133], v[182:185], v[22:25]
	v_mfma_f32_16x16x32_bf16 v[38:41], v[138:141], v[182:185], v[38:41]
	v_mfma_f32_16x16x32_bf16 v[10:13], v[134:137], v[170:173], v[10:13]
	v_mfma_f32_16x16x32_bf16 v[6:9], v[142:145], v[170:173], v[6:9]
	v_mfma_f32_16x16x32_bf16 v[2:5], v[134:137], v[174:177], v[2:5]
	v_mfma_f32_16x16x32_bf16 v[18:21], v[142:145], v[174:177], v[18:21]
	v_mfma_f32_16x16x32_bf16 v[14:17], v[134:137], v[186:189], v[14:17]
	v_mfma_f32_16x16x32_bf16 v[26:29], v[142:145], v[186:189], v[26:29]
	v_mfma_f32_16x16x32_bf16 v[22:25], v[134:137], v[190:193], v[22:25]
	v_mfma_f32_16x16x32_bf16 v[38:41], v[142:145], v[190:193], v[38:41]
	v_mfma_f32_16x16x32_bf16 v[34:37], v[146:149], v[162:165], v[34:37]
	v_mfma_f32_16x16x32_bf16 v[30:33], v[154:157], v[162:165], v[30:33]
	v_mfma_f32_16x16x32_bf16 v[42:45], v[146:149], v[166:169], v[42:45]
	v_mfma_f32_16x16x32_bf16 v[46:49], v[154:157], v[166:169], v[46:49]
	v_mfma_f32_16x16x32_bf16 v[50:53], v[146:149], v[178:181], v[50:53]
	v_mfma_f32_16x16x32_bf16 v[54:57], v[154:157], v[178:181], v[54:57]
	v_mfma_f32_16x16x32_bf16 v[58:61], v[146:149], v[182:185], v[58:61]
	v_mfma_f32_16x16x32_bf16 v[62:65], v[154:157], v[182:185], v[62:65]
	v_mfma_f32_16x16x32_bf16 v[34:37], v[150:153], v[170:173], v[34:37]
	v_mfma_f32_16x16x32_bf16 v[30:33], v[158:161], v[170:173], v[30:33]
	v_mfma_f32_16x16x32_bf16 v[42:45], v[150:153], v[174:177], v[42:45]
	v_mfma_f32_16x16x32_bf16 v[46:49], v[158:161], v[174:177], v[46:49]
	v_mfma_f32_16x16x32_bf16 v[50:53], v[150:153], v[186:189], v[50:53]
	v_mfma_f32_16x16x32_bf16 v[54:57], v[158:161], v[186:189], v[54:57]
	v_mfma_f32_16x16x32_bf16 v[58:61], v[150:153], v[190:193], v[58:61]
	v_mfma_f32_16x16x32_bf16 v[62:65], v[158:161], v[190:193], v[62:65]
	s_barrier
	s_setprio 0
	s_add_i32 s4, s4, 2
	s_addk_i32 s5, 0x100
	s_cmp_gt_u32 s4, 13
	s_cbranch_scc0 .LBB0_841
	s_and_b64 vcc, exec, s[16:17]
	s_cbranch_vccz .LBB0_844
	s_barrier

.LBB0_1122:
	ds_read_b128 v[130:133], v240
	ds_read_b128 v[134:137], v241
	ds_read_b128 v[138:141], v242
	ds_read_b128 v[142:145], v243
	ds_read_b128 v[146:149], v244
	ds_read_b128 v[150:153], v245
	ds_read_b128 v[154:157], v246
	ds_read_b128 v[158:161], v247
	s_add_i32 s8, s31, s53
	s_add_i32 s55, s26, s53
	s_add_i32 s54, s8, 0x800
	s_addk_i32 s55, 0x800
	s_cmp_eq_u32 s53, 0
	s_cselect_b32 s56, s4, s54
	s_cselect_b32 s55, s5, s55
	s_add_i32 s54, s56, 0x80
	s_add_i32 s57, s8, 0x40780
	s_mov_b32 s8, s70
	s_mov_b32 m0, s44
	ds_read_b128 v[162:165], v248
	ds_read_b128 v[166:169], v248 offset:2048
	ds_read_b128 v[170:173], v249
	ds_read_b128 v[174:177], v249 offset:2048
	ds_read_b128 v[178:181], v248 offset:4096
	ds_read_b128 v[182:185], v248 offset:6144
	ds_read_b128 v[186:189], v249 offset:4096
	ds_read_b128 v[190:193], v249 offset:6144
	buffer_load_dwordx4 v1, s[8:11], s57 offen lds
	s_mov_b32 m0, s45
	s_nop 0
	buffer_load_dwordx4 v234, s[8:11], s57 offen lds
	s_waitcnt vmcnt(8)
	s_waitcnt lgkmcnt(0)
	s_setprio 1
	v_mfma_f32_16x16x32_bf16 v[126:129], v[130:133], v[162:165], v[126:129]
	v_mfma_f32_16x16x32_bf16 v[122:125], v[138:141], v[162:165], v[122:125]
	v_mfma_f32_16x16x32_bf16 v[118:121], v[130:133], v[166:169], v[118:121]
	v_mfma_f32_16x16x32_bf16 v[114:117], v[138:141], v[166:169], v[114:117]
	s_barrier
	v_mfma_f32_16x16x32_bf16 v[110:113], v[130:133], v[178:181], v[110:113]
	v_mfma_f32_16x16x32_bf16 v[106:109], v[138:141], v[178:181], v[106:109]
	v_mfma_f32_16x16x32_bf16 v[102:105], v[130:133], v[182:185], v[102:105]
	v_mfma_f32_16x16x32_bf16 v[98:101], v[138:141], v[182:185], v[98:101]
	v_mfma_f32_16x16x32_bf16 v[126:129], v[134:137], v[170:173], v[126:129]
	v_mfma_f32_16x16x32_bf16 v[122:125], v[142:145], v[170:173], v[122:125]
	v_mfma_f32_16x16x32_bf16 v[118:121], v[134:137], v[174:177], v[118:121]
	v_mfma_f32_16x16x32_bf16 v[114:117], v[142:145], v[174:177], v[114:117]
	v_mfma_f32_16x16x32_bf16 v[110:113], v[134:137], v[186:189], v[110:113]
	v_mfma_f32_16x16x32_bf16 v[106:109], v[142:145], v[186:189], v[106:109]
	v_mfma_f32_16x16x32_bf16 v[102:105], v[134:137], v[190:193], v[102:105]
	v_mfma_f32_16x16x32_bf16 v[98:101], v[142:145], v[190:193], v[98:101]
	v_mfma_f32_16x16x32_bf16 v[94:97], v[146:149], v[162:165], v[94:97]
	v_mfma_f32_16x16x32_bf16 v[90:93], v[154:157], v[162:165], v[90:93]
	v_mfma_f32_16x16x32_bf16 v[86:89], v[146:149], v[166:169], v[86:89]
	v_mfma_f32_16x16x32_bf16 v[82:85], v[154:157], v[166:169], v[82:85]
	v_mfma_f32_16x16x32_bf16 v[78:81], v[146:149], v[178:181], v[78:81]
	v_mfma_f32_16x16x32_bf16 v[74:77], v[154:157], v[178:181], v[74:77]
	v_mfma_f32_16x16x32_bf16 v[70:73], v[146:149], v[182:185], v[70:73]
	v_mfma_f32_16x16x32_bf16 v[66:69], v[154:157], v[182:185], v[66:69]
	v_mfma_f32_16x16x32_bf16 v[94:97], v[150:153], v[170:173], v[94:97]
	v_mfma_f32_16x16x32_bf16 v[90:93], v[158:161], v[170:173], v[90:93]
	v_mfma_f32_16x16x32_bf16 v[86:89], v[150:153], v[174:177], v[86:89]
	v_mfma_f32_16x16x32_bf16 v[82:85], v[158:161], v[174:177], v[82:85]
	v_mfma_f32_16x16x32_bf16 v[78:81], v[150:153], v[186:189], v[78:81]
	v_mfma_f32_16x16x32_bf16 v[74:77], v[158:161], v[186:189], v[74:77]
	v_mfma_f32_16x16x32_bf16 v[70:73], v[150:153], v[190:193], v[70:73]
	v_mfma_f32_16x16x32_bf16 v[66:69], v[158:161], v[190:193], v[66:69]
	s_barrier
	s_setprio 0
	s_mov_b32 m0, s23
	ds_read_b128 v[162:165], v248 offset:16384
	ds_read_b128 v[166:169], v248 offset:18432
	ds_read_b128 v[170:173], v249 offset:16384
	ds_read_b128 v[174:177], v249 offset:18432
	ds_read_b128 v[178:181], v248 offset:20480
	ds_read_b128 v[182:185], v248 offset:22528
	ds_read_b128 v[186:189], v249 offset:20480
	ds_read_b128 v[190:193], v249 offset:22528
	buffer_load_dwordx4 v233, s[8:11], s55 offen lds
	s_mov_b32 m0, s24
	s_add_i32 s57, s55, 0x40000
	buffer_load_dwordx4 v235, s[8:11], s55 offen lds
	s_mov_b32 m0, s25
	s_nop 0
	buffer_load_dwordx4 v233, s[8:11], s57 offen lds
	s_mov_b32 m0, s27
	s_nop 0
	buffer_load_dwordx4 v235, s[8:11], s57 offen lds
	s_mov_b32 m0, s22
	s_nop 0
	buffer_load_dwordx4 v1, s[8:11], s56 offen lds
	s_mov_b32 m0, s28
	s_nop 0
	buffer_load_dwordx4 v234, s[8:11], s56 offen lds
	s_waitcnt vmcnt(8)
	s_waitcnt lgkmcnt(0)
	s_setprio 1
	s_barrier
	v_mfma_f32_16x16x32_bf16 v[62:65], v[130:133], v[162:165], v[62:65]
	v_mfma_f32_16x16x32_bf16 v[58:61], v[138:141], v[162:165], v[58:61]
	v_mfma_f32_16x16x32_bf16 v[54:57], v[130:133], v[166:169], v[54:57]
	v_mfma_f32_16x16x32_bf16 v[50:53], v[138:141], v[166:169], v[50:53]
	v_mfma_f32_16x16x32_bf16 v[46:49], v[130:133], v[178:181], v[46:49]
	v_mfma_f32_16x16x32_bf16 v[42:45], v[138:141], v[178:181], v[42:45]
	v_mfma_f32_16x16x32_bf16 v[38:41], v[130:133], v[182:185], v[38:41]
	v_mfma_f32_16x16x32_bf16 v[34:37], v[138:141], v[182:185], v[34:37]
	v_mfma_f32_16x16x32_bf16 v[62:65], v[134:137], v[170:173], v[62:65]
	v_mfma_f32_16x16x32_bf16 v[58:61], v[142:145], v[170:173], v[58:61]
	v_mfma_f32_16x16x32_bf16 v[54:57], v[134:137], v[174:177], v[54:57]
	v_mfma_f32_16x16x32_bf16 v[50:53], v[142:145], v[174:177], v[50:53]
	v_mfma_f32_16x16x32_bf16 v[46:49], v[134:137], v[186:189], v[46:49]
	v_mfma_f32_16x16x32_bf16 v[42:45], v[142:145], v[186:189], v[42:45]
	v_mfma_f32_16x16x32_bf16 v[38:41], v[134:137], v[190:193], v[38:41]
	v_mfma_f32_16x16x32_bf16 v[34:37], v[142:145], v[190:193], v[34:37]
	v_mfma_f32_16x16x32_bf16 v[30:33], v[146:149], v[162:165], v[30:33]
	v_mfma_f32_16x16x32_bf16 v[26:29], v[154:157], v[162:165], v[26:29]
	v_mfma_f32_16x16x32_bf16 v[22:25], v[146:149], v[166:169], v[22:25]
	v_mfma_f32_16x16x32_bf16 v[18:21], v[154:157], v[166:169], v[18:21]
	v_mfma_f32_16x16x32_bf16 v[14:17], v[146:149], v[178:181], v[14:17]
	v_mfma_f32_16x16x32_bf16 v[10:13], v[154:157], v[178:181], v[10:13]
	v_mfma_f32_16x16x32_bf16 v[6:9], v[146:149], v[182:185], v[6:9]
	v_mfma_f32_16x16x32_bf16 v[2:5], v[154:157], v[182:185], v[2:5]
	v_mfma_f32_16x16x32_bf16 v[30:33], v[150:153], v[170:173], v[30:33]
	v_mfma_f32_16x16x32_bf16 v[26:29], v[158:161], v[170:173], v[26:29]
	v_mfma_f32_16x16x32_bf16 v[22:25], v[150:153], v[174:177], v[22:25]
	v_mfma_f32_16x16x32_bf16 v[18:21], v[158:161], v[174:177], v[18:21]
	v_mfma_f32_16x16x32_bf16 v[14:17], v[150:153], v[186:189], v[14:17]
	v_mfma_f32_16x16x32_bf16 v[10:13], v[158:161], v[186:189], v[10:13]
	v_mfma_f32_16x16x32_bf16 v[6:9], v[150:153], v[190:193], v[6:9]
	v_mfma_f32_16x16x32_bf16 v[2:5], v[158:161], v[190:193], v[2:5]
	s_barrier
	s_setprio 0
	ds_read_b128 v[130:133], v194
	ds_read_b128 v[134:137], v195
	ds_read_b128 v[138:141], v196
	ds_read_b128 v[142:145], v197
	ds_read_b128 v[146:149], v198
	ds_read_b128 v[150:153], v199
	ds_read_b128 v[154:157], v200
	ds_read_b128 v[158:161], v201
	s_add_i32 s56, s56, 0x40000
	s_mov_b32 m0, s29
	ds_read_b128 v[162:165], v248 offset:32768
	ds_read_b128 v[166:169], v248 offset:34816
	ds_read_b128 v[170:173], v249 offset:32768
	ds_read_b128 v[174:177], v249 offset:34816
	ds_read_b128 v[178:181], v248 offset:36864
	ds_read_b128 v[182:185], v248 offset:38912
	ds_read_b128 v[186:189], v249 offset:36864
	ds_read_b128 v[190:193], v249 offset:38912
	buffer_load_dwordx4 v1, s[8:11], s56 offen lds
	s_mov_b32 m0, s30
	s_nop 0
	buffer_load_dwordx4 v234, s[8:11], s56 offen lds
	s_waitcnt vmcnt(8)
	s_waitcnt lgkmcnt(0)
	s_setprio 1
	v_mfma_f32_16x16x32_bf16 v[126:129], v[130:133], v[162:165], v[126:129]
	v_mfma_f32_16x16x32_bf16 v[122:125], v[138:141], v[162:165], v[122:125]
	v_mfma_f32_16x16x32_bf16 v[118:121], v[130:133], v[166:169], v[118:121]
	v_mfma_f32_16x16x32_bf16 v[114:117], v[138:141], v[166:169], v[114:117]
	s_barrier
	v_mfma_f32_16x16x32_bf16 v[110:113], v[130:133], v[178:181], v[110:113]
	v_mfma_f32_16x16x32_bf16 v[106:109], v[138:141], v[178:181], v[106:109]
	v_mfma_f32_16x16x32_bf16 v[102:105], v[130:133], v[182:185], v[102:105]
	v_mfma_f32_16x16x32_bf16 v[98:101], v[138:141], v[182:185], v[98:101]
	v_mfma_f32_16x16x32_bf16 v[126:129], v[134:137], v[170:173], v[126:129]
	v_mfma_f32_16x16x32_bf16 v[122:125], v[142:145], v[170:173], v[122:125]
	v_mfma_f32_16x16x32_bf16 v[118:121], v[134:137], v[174:177], v[118:121]
	v_mfma_f32_16x16x32_bf16 v[114:117], v[142:145], v[174:177], v[114:117]
	v_mfma_f32_16x16x32_bf16 v[110:113], v[134:137], v[186:189], v[110:113]
	v_mfma_f32_16x16x32_bf16 v[106:109], v[142:145], v[186:189], v[106:109]
	v_mfma_f32_16x16x32_bf16 v[102:105], v[134:137], v[190:193], v[102:105]
	v_mfma_f32_16x16x32_bf16 v[98:101], v[142:145], v[190:193], v[98:101]
	v_mfma_f32_16x16x32_bf16 v[94:97], v[146:149], v[162:165], v[94:97]
	v_mfma_f32_16x16x32_bf16 v[90:93], v[154:157], v[162:165], v[90:93]
	v_mfma_f32_16x16x32_bf16 v[86:89], v[146:149], v[166:169], v[86:89]
	v_mfma_f32_16x16x32_bf16 v[82:85], v[154:157], v[166:169], v[82:85]
	v_mfma_f32_16x16x32_bf16 v[78:81], v[146:149], v[178:181], v[78:81]
	v_mfma_f32_16x16x32_bf16 v[74:77], v[154:157], v[178:181], v[74:77]
	v_mfma_f32_16x16x32_bf16 v[70:73], v[146:149], v[182:185], v[70:73]
	v_mfma_f32_16x16x32_bf16 v[66:69], v[154:157], v[182:185], v[66:69]
	v_mfma_f32_16x16x32_bf16 v[94:97], v[150:153], v[170:173], v[94:97]
	v_mfma_f32_16x16x32_bf16 v[90:93], v[158:161], v[170:173], v[90:93]
	v_mfma_f32_16x16x32_bf16 v[86:89], v[150:153], v[174:177], v[86:89]
	v_mfma_f32_16x16x32_bf16 v[82:85], v[158:161], v[174:177], v[82:85]
	v_mfma_f32_16x16x32_bf16 v[78:81], v[150:153], v[186:189], v[78:81]
	v_mfma_f32_16x16x32_bf16 v[74:77], v[158:161], v[186:189], v[74:77]
	v_mfma_f32_16x16x32_bf16 v[70:73], v[150:153], v[190:193], v[70:73]
	v_mfma_f32_16x16x32_bf16 v[66:69], v[158:161], v[190:193], v[66:69]
	s_barrier
	s_setprio 0
	s_mov_b32 m0, s35
	s_add_i32 s56, s55, 0x80
	ds_read_b128 v[162:165], v248 offset:49152
	ds_read_b128 v[166:169], v248 offset:51200
	ds_read_b128 v[170:173], v249 offset:49152
	ds_read_b128 v[174:177], v249 offset:51200
	ds_read_b128 v[178:181], v248 offset:53248
	ds_read_b128 v[182:185], v248 offset:55296
	ds_read_b128 v[186:189], v249 offset:53248
	ds_read_b128 v[190:193], v249 offset:55296
	buffer_load_dwordx4 v233, s[8:11], s56 offen lds
	s_mov_b32 m0, s36
	s_add_i32 s55, s55, 0x40080
	buffer_load_dwordx4 v235, s[8:11], s56 offen lds
	s_mov_b32 m0, s39
	s_nop 0
	buffer_load_dwordx4 v233, s[8:11], s55 offen lds
	s_mov_b32 m0, s41
	s_nop 0
	buffer_load_dwordx4 v235, s[8:11], s55 offen lds
	s_mov_b32 m0, s37
	s_nop 0
	buffer_load_dwordx4 v1, s[8:11], s54 offen lds
	s_mov_b32 m0, s38
	s_nop 0
	buffer_load_dwordx4 v234, s[8:11], s54 offen lds
	s_waitcnt vmcnt(8)
	s_waitcnt lgkmcnt(0)
	s_setprio 1
	s_barrier
	v_mfma_f32_16x16x32_bf16 v[62:65], v[130:133], v[162:165], v[62:65]
	v_mfma_f32_16x16x32_bf16 v[58:61], v[138:141], v[162:165], v[58:61]
	v_mfma_f32_16x16x32_bf16 v[54:57], v[130:133], v[166:169], v[54:57]
	v_mfma_f32_16x16x32_bf16 v[50:53], v[138:141], v[166:169], v[50:53]
	v_mfma_f32_16x16x32_bf16 v[46:49], v[130:133], v[178:181], v[46:49]
	v_mfma_f32_16x16x32_bf16 v[42:45], v[138:141], v[178:181], v[42:45]
	v_mfma_f32_16x16x32_bf16 v[38:41], v[130:133], v[182:185], v[38:41]
	v_mfma_f32_16x16x32_bf16 v[34:37], v[138:141], v[182:185], v[34:37]
	v_mfma_f32_16x16x32_bf16 v[62:65], v[134:137], v[170:173], v[62:65]
	v_mfma_f32_16x16x32_bf16 v[58:61], v[142:145], v[170:173], v[58:61]
	v_mfma_f32_16x16x32_bf16 v[54:57], v[134:137], v[174:177], v[54:57]
	v_mfma_f32_16x16x32_bf16 v[50:53], v[142:145], v[174:177], v[50:53]
	v_mfma_f32_16x16x32_bf16 v[46:49], v[134:137], v[186:189], v[46:49]
	v_mfma_f32_16x16x32_bf16 v[42:45], v[142:145], v[186:189], v[42:45]
	v_mfma_f32_16x16x32_bf16 v[38:41], v[134:137], v[190:193], v[38:41]
	v_mfma_f32_16x16x32_bf16 v[34:37], v[142:145], v[190:193], v[34:37]
	v_mfma_f32_16x16x32_bf16 v[30:33], v[146:149], v[162:165], v[30:33]
	v_mfma_f32_16x16x32_bf16 v[26:29], v[154:157], v[162:165], v[26:29]
	v_mfma_f32_16x16x32_bf16 v[22:25], v[146:149], v[166:169], v[22:25]
	v_mfma_f32_16x16x32_bf16 v[18:21], v[154:157], v[166:169], v[18:21]
	v_mfma_f32_16x16x32_bf16 v[14:17], v[146:149], v[178:181], v[14:17]
	v_mfma_f32_16x16x32_bf16 v[10:13], v[154:157], v[178:181], v[10:13]
	v_mfma_f32_16x16x32_bf16 v[6:9], v[146:149], v[182:185], v[6:9]
	v_mfma_f32_16x16x32_bf16 v[2:5], v[154:157], v[182:185], v[2:5]
	v_mfma_f32_16x16x32_bf16 v[30:33], v[150:153], v[170:173], v[30:33]
	v_mfma_f32_16x16x32_bf16 v[26:29], v[158:161], v[170:173], v[26:29]
	v_mfma_f32_16x16x32_bf16 v[22:25], v[150:153], v[174:177], v[22:25]
	v_mfma_f32_16x16x32_bf16 v[18:21], v[158:161], v[174:177], v[18:21]
	v_mfma_f32_16x16x32_bf16 v[14:17], v[150:153], v[186:189], v[14:17]
	v_mfma_f32_16x16x32_bf16 v[10:13], v[158:161], v[186:189], v[10:13]
	v_mfma_f32_16x16x32_bf16 v[6:9], v[150:153], v[190:193], v[6:9]
	v_mfma_f32_16x16x32_bf16 v[2:5], v[158:161], v[190:193], v[2:5]
	s_barrier
	s_setprio 0
	s_add_i32 s33, s33, 2
	s_addk_i32 s53, 0x100
	s_cmp_gt_u32 s33, 13
	s_cbranch_scc0 .LBB0_1122
	s_and_b64 vcc, exec, s[16:17]
	s_cbranch_vccz .LBB0_1125
	s_barrier

.LBB0_1251:
	ds_read_b128 v[130:133], v239
	ds_read_b128 v[134:137], v240
	ds_read_b128 v[138:141], v241
	ds_read_b128 v[142:145], v242
	ds_read_b128 v[146:149], v243
	ds_read_b128 v[150:153], v244
	ds_read_b128 v[154:157], v245
	ds_read_b128 v[158:161], v246
	s_add_i32 s8, s51, s5
	s_add_i32 s31, s46, s5
	s_add_i32 s30, s8, 0x2000
	s_addk_i32 s31, 0x2000
	s_cmp_eq_u32 s5, 0
	s_cselect_b32 s33, s0, s30
	s_cselect_b32 s31, s1, s31
	s_add_i32 s30, s33, 0x80
	s_add_i32 s34, s8, 0x101f80
	s_mov_b32 s8, s70
	s_mov_b32 m0, s61
	ds_read_b128 v[162:165], v247
	ds_read_b128 v[166:169], v247 offset:2048
	ds_read_b128 v[170:173], v248
	ds_read_b128 v[174:177], v248 offset:2048
	ds_read_b128 v[178:181], v247 offset:4096
	ds_read_b128 v[182:185], v247 offset:6144
	ds_read_b128 v[186:189], v248 offset:4096
	ds_read_b128 v[190:193], v248 offset:6144
	buffer_load_dwordx4 v230, s[8:11], s34 offen lds
	s_mov_b32 m0, s64
	s_nop 0
	buffer_load_dwordx4 v233, s[8:11], s34 offen lds
	s_waitcnt vmcnt(8)
	s_waitcnt lgkmcnt(0)
	s_setprio 1
	v_mfma_f32_16x16x32_bf16 v[74:77], v[130:133], v[162:165], v[74:77]
	v_mfma_f32_16x16x32_bf16 v[70:73], v[138:141], v[162:165], v[70:73]
	v_mfma_f32_16x16x32_bf16 v[66:69], v[130:133], v[166:169], v[66:69]
	v_mfma_f32_16x16x32_bf16 v[82:85], v[138:141], v[166:169], v[82:85]
	s_barrier
	v_mfma_f32_16x16x32_bf16 v[78:81], v[130:133], v[178:181], v[78:81]
	v_mfma_f32_16x16x32_bf16 v[90:93], v[138:141], v[178:181], v[90:93]
	v_mfma_f32_16x16x32_bf16 v[86:89], v[130:133], v[182:185], v[86:89]
	v_mfma_f32_16x16x32_bf16 v[102:105], v[138:141], v[182:185], v[102:105]
	v_mfma_f32_16x16x32_bf16 v[74:77], v[134:137], v[170:173], v[74:77]
	v_mfma_f32_16x16x32_bf16 v[70:73], v[142:145], v[170:173], v[70:73]
	v_mfma_f32_16x16x32_bf16 v[66:69], v[134:137], v[174:177], v[66:69]
	v_mfma_f32_16x16x32_bf16 v[82:85], v[142:145], v[174:177], v[82:85]
	v_mfma_f32_16x16x32_bf16 v[78:81], v[134:137], v[186:189], v[78:81]
	v_mfma_f32_16x16x32_bf16 v[90:93], v[142:145], v[186:189], v[90:93]
	v_mfma_f32_16x16x32_bf16 v[86:89], v[134:137], v[190:193], v[86:89]
	v_mfma_f32_16x16x32_bf16 v[102:105], v[142:145], v[190:193], v[102:105]
	v_mfma_f32_16x16x32_bf16 v[98:101], v[146:149], v[162:165], v[98:101]
	v_mfma_f32_16x16x32_bf16 v[94:97], v[154:157], v[162:165], v[94:97]
	v_mfma_f32_16x16x32_bf16 v[106:109], v[146:149], v[166:169], v[106:109]
	v_mfma_f32_16x16x32_bf16 v[110:113], v[154:157], v[166:169], v[110:113]
	v_mfma_f32_16x16x32_bf16 v[114:117], v[146:149], v[178:181], v[114:117]
	v_mfma_f32_16x16x32_bf16 v[118:121], v[154:157], v[178:181], v[118:121]
	v_mfma_f32_16x16x32_bf16 v[122:125], v[146:149], v[182:185], v[122:125]
	v_mfma_f32_16x16x32_bf16 v[126:129], v[154:157], v[182:185], v[126:129]
	v_mfma_f32_16x16x32_bf16 v[98:101], v[150:153], v[170:173], v[98:101]
	v_mfma_f32_16x16x32_bf16 v[94:97], v[158:161], v[170:173], v[94:97]
	v_mfma_f32_16x16x32_bf16 v[106:109], v[150:153], v[174:177], v[106:109]
	v_mfma_f32_16x16x32_bf16 v[110:113], v[158:161], v[174:177], v[110:113]
	v_mfma_f32_16x16x32_bf16 v[114:117], v[150:153], v[186:189], v[114:117]
	v_mfma_f32_16x16x32_bf16 v[118:121], v[158:161], v[186:189], v[118:121]
	v_mfma_f32_16x16x32_bf16 v[122:125], v[150:153], v[190:193], v[122:125]
	v_mfma_f32_16x16x32_bf16 v[126:129], v[158:161], v[190:193], v[126:129]
	s_barrier
	s_setprio 0
	s_mov_b32 m0, s43
	ds_read_b128 v[162:165], v247 offset:16384
	ds_read_b128 v[166:169], v247 offset:18432
	ds_read_b128 v[170:173], v248 offset:16384
	ds_read_b128 v[174:177], v248 offset:18432
	ds_read_b128 v[178:181], v247 offset:20480
	ds_read_b128 v[182:185], v247 offset:22528
	ds_read_b128 v[186:189], v248 offset:20480
	ds_read_b128 v[190:193], v248 offset:22528
	buffer_load_dwordx4 v231, s[8:11], s31 offen lds
	s_mov_b32 m0, s44
	s_add_i32 s34, s31, 0x100000
	buffer_load_dwordx4 v234, s[8:11], s31 offen lds
	s_mov_b32 m0, s45
	s_nop 0
	buffer_load_dwordx4 v231, s[8:11], s34 offen lds
	s_mov_b32 m0, s47
	s_nop 0
	buffer_load_dwordx4 v234, s[8:11], s34 offen lds
	s_mov_b32 m0, s42
	s_nop 0
	buffer_load_dwordx4 v230, s[8:11], s33 offen lds
	s_mov_b32 m0, s48
	s_nop 0
	buffer_load_dwordx4 v233, s[8:11], s33 offen lds
	s_waitcnt vmcnt(8)
	s_waitcnt lgkmcnt(0)
	s_setprio 1
	s_barrier
	v_mfma_f32_16x16x32_bf16 v[10:13], v[130:133], v[162:165], v[10:13]
	v_mfma_f32_16x16x32_bf16 v[6:9], v[138:141], v[162:165], v[6:9]
	v_mfma_f32_16x16x32_bf16 v[0:3], v[130:133], v[166:169], v[2:5]
	v_mfma_f32_16x16x32_bf16 v[18:21], v[138:141], v[166:169], v[18:21]
	v_mfma_f32_16x16x32_bf16 v[14:17], v[130:133], v[178:181], v[14:17]
	v_mfma_f32_16x16x32_bf16 v[26:29], v[138:141], v[178:181], v[26:29]
	v_mfma_f32_16x16x32_bf16 v[22:25], v[130:133], v[182:185], v[22:25]
	v_mfma_f32_16x16x32_bf16 v[38:41], v[138:141], v[182:185], v[38:41]
	v_mfma_f32_16x16x32_bf16 v[10:13], v[134:137], v[170:173], v[10:13]
	v_mfma_f32_16x16x32_bf16 v[6:9], v[142:145], v[170:173], v[6:9]
	v_mfma_f32_16x16x32_bf16 v[0:3], v[134:137], v[174:177], v[0:3]
	v_mfma_f32_16x16x32_bf16 v[18:21], v[142:145], v[174:177], v[18:21]
	v_mfma_f32_16x16x32_bf16 v[14:17], v[134:137], v[186:189], v[14:17]
	v_mfma_f32_16x16x32_bf16 v[26:29], v[142:145], v[186:189], v[26:29]
	v_mfma_f32_16x16x32_bf16 v[22:25], v[134:137], v[190:193], v[22:25]
	v_mfma_f32_16x16x32_bf16 v[38:41], v[142:145], v[190:193], v[38:41]
	v_mfma_f32_16x16x32_bf16 v[34:37], v[146:149], v[162:165], v[34:37]
	v_mfma_f32_16x16x32_bf16 v[30:33], v[154:157], v[162:165], v[30:33]
	v_mfma_f32_16x16x32_bf16 v[42:45], v[146:149], v[166:169], v[42:45]
	v_mfma_f32_16x16x32_bf16 v[46:49], v[154:157], v[166:169], v[46:49]
	v_mfma_f32_16x16x32_bf16 v[50:53], v[146:149], v[178:181], v[50:53]
	v_mfma_f32_16x16x32_bf16 v[54:57], v[154:157], v[178:181], v[54:57]
	v_mfma_f32_16x16x32_bf16 v[58:61], v[146:149], v[182:185], v[58:61]
	v_mfma_f32_16x16x32_bf16 v[62:65], v[154:157], v[182:185], v[62:65]
	v_mfma_f32_16x16x32_bf16 v[34:37], v[150:153], v[170:173], v[34:37]
	v_mfma_f32_16x16x32_bf16 v[30:33], v[158:161], v[170:173], v[30:33]
	v_mfma_f32_16x16x32_bf16 v[42:45], v[150:153], v[174:177], v[42:45]
	v_mfma_f32_16x16x32_bf16 v[46:49], v[158:161], v[174:177], v[46:49]
	v_mfma_f32_16x16x32_bf16 v[50:53], v[150:153], v[186:189], v[50:53]
	v_mfma_f32_16x16x32_bf16 v[54:57], v[158:161], v[186:189], v[54:57]
	v_mfma_f32_16x16x32_bf16 v[58:61], v[150:153], v[190:193], v[58:61]
	v_mfma_f32_16x16x32_bf16 v[62:65], v[158:161], v[190:193], v[62:65]
	s_barrier
	s_setprio 0
	ds_read_b128 v[130:133], v194
	ds_read_b128 v[134:137], v195
	ds_read_b128 v[138:141], v196
	ds_read_b128 v[142:145], v197
	ds_read_b128 v[146:149], v198
	ds_read_b128 v[150:153], v199
	ds_read_b128 v[154:157], v200
	ds_read_b128 v[158:161], v201
	s_add_i32 s33, s33, 0x100000
	s_mov_b32 m0, s49
	ds_read_b128 v[162:165], v247 offset:32768
	ds_read_b128 v[166:169], v247 offset:34816
	ds_read_b128 v[170:173], v248 offset:32768
	ds_read_b128 v[174:177], v248 offset:34816
	ds_read_b128 v[178:181], v247 offset:36864
	ds_read_b128 v[182:185], v247 offset:38912
	ds_read_b128 v[186:189], v248 offset:36864
	ds_read_b128 v[190:193], v248 offset:38912
	buffer_load_dwordx4 v230, s[8:11], s33 offen lds
	s_mov_b32 m0, s50
	s_nop 0
	buffer_load_dwordx4 v233, s[8:11], s33 offen lds
	s_waitcnt vmcnt(8)
	s_waitcnt lgkmcnt(0)
	s_setprio 1
	v_mfma_f32_16x16x32_bf16 v[74:77], v[130:133], v[162:165], v[74:77]
	v_mfma_f32_16x16x32_bf16 v[70:73], v[138:141], v[162:165], v[70:73]
	v_mfma_f32_16x16x32_bf16 v[66:69], v[130:133], v[166:169], v[66:69]
	v_mfma_f32_16x16x32_bf16 v[82:85], v[138:141], v[166:169], v[82:85]
	s_barrier
	v_mfma_f32_16x16x32_bf16 v[78:81], v[130:133], v[178:181], v[78:81]
	v_mfma_f32_16x16x32_bf16 v[90:93], v[138:141], v[178:181], v[90:93]
	v_mfma_f32_16x16x32_bf16 v[86:89], v[130:133], v[182:185], v[86:89]
	v_mfma_f32_16x16x32_bf16 v[102:105], v[138:141], v[182:185], v[102:105]
	v_mfma_f32_16x16x32_bf16 v[74:77], v[134:137], v[170:173], v[74:77]
	v_mfma_f32_16x16x32_bf16 v[70:73], v[142:145], v[170:173], v[70:73]
	v_mfma_f32_16x16x32_bf16 v[66:69], v[134:137], v[174:177], v[66:69]
	v_mfma_f32_16x16x32_bf16 v[82:85], v[142:145], v[174:177], v[82:85]
	v_mfma_f32_16x16x32_bf16 v[78:81], v[134:137], v[186:189], v[78:81]
	v_mfma_f32_16x16x32_bf16 v[90:93], v[142:145], v[186:189], v[90:93]
	v_mfma_f32_16x16x32_bf16 v[86:89], v[134:137], v[190:193], v[86:89]
	v_mfma_f32_16x16x32_bf16 v[102:105], v[142:145], v[190:193], v[102:105]
	v_mfma_f32_16x16x32_bf16 v[98:101], v[146:149], v[162:165], v[98:101]
	v_mfma_f32_16x16x32_bf16 v[94:97], v[154:157], v[162:165], v[94:97]
	v_mfma_f32_16x16x32_bf16 v[106:109], v[146:149], v[166:169], v[106:109]
	v_mfma_f32_16x16x32_bf16 v[110:113], v[154:157], v[166:169], v[110:113]
	v_mfma_f32_16x16x32_bf16 v[114:117], v[146:149], v[178:181], v[114:117]
	v_mfma_f32_16x16x32_bf16 v[118:121], v[154:157], v[178:181], v[118:121]
	v_mfma_f32_16x16x32_bf16 v[122:125], v[146:149], v[182:185], v[122:125]
	v_mfma_f32_16x16x32_bf16 v[126:129], v[154:157], v[182:185], v[126:129]
	v_mfma_f32_16x16x32_bf16 v[98:101], v[150:153], v[170:173], v[98:101]
	v_mfma_f32_16x16x32_bf16 v[94:97], v[158:161], v[170:173], v[94:97]
	v_mfma_f32_16x16x32_bf16 v[106:109], v[150:153], v[174:177], v[106:109]
	v_mfma_f32_16x16x32_bf16 v[110:113], v[158:161], v[174:177], v[110:113]
	v_mfma_f32_16x16x32_bf16 v[114:117], v[150:153], v[186:189], v[114:117]
	v_mfma_f32_16x16x32_bf16 v[118:121], v[158:161], v[186:189], v[118:121]
	v_mfma_f32_16x16x32_bf16 v[122:125], v[150:153], v[190:193], v[122:125]
	v_mfma_f32_16x16x32_bf16 v[126:129], v[158:161], v[190:193], v[126:129]
	s_barrier
	s_setprio 0
	s_mov_b32 m0, s53
	s_add_i32 s33, s31, 0x80
	ds_read_b128 v[162:165], v247 offset:49152
	ds_read_b128 v[166:169], v247 offset:51200
	ds_read_b128 v[170:173], v248 offset:49152
	ds_read_b128 v[174:177], v248 offset:51200
	ds_read_b128 v[178:181], v247 offset:53248
	ds_read_b128 v[182:185], v247 offset:55296
	ds_read_b128 v[186:189], v248 offset:53248
	ds_read_b128 v[190:193], v248 offset:55296
	buffer_load_dwordx4 v231, s[8:11], s33 offen lds
	s_mov_b32 m0, s54
	s_add_i32 s31, s31, 0x100080
	buffer_load_dwordx4 v234, s[8:11], s33 offen lds
	s_mov_b32 m0, s57
	s_nop 0
	buffer_load_dwordx4 v231, s[8:11], s31 offen lds
	s_mov_b32 m0, s58
	s_nop 0
	buffer_load_dwordx4 v234, s[8:11], s31 offen lds
	s_mov_b32 m0, s55
	s_nop 0
	buffer_load_dwordx4 v230, s[8:11], s30 offen lds
	s_mov_b32 m0, s56
	s_nop 0
	buffer_load_dwordx4 v233, s[8:11], s30 offen lds
	s_waitcnt vmcnt(8)
	s_waitcnt lgkmcnt(0)
	s_setprio 1
	s_barrier
	v_mfma_f32_16x16x32_bf16 v[10:13], v[130:133], v[162:165], v[10:13]
	v_mfma_f32_16x16x32_bf16 v[4:7], v[138:141], v[162:165], v[6:9]
	v_mfma_f32_16x16x32_bf16 v[0:3], v[130:133], v[166:169], v[0:3]
	v_mfma_f32_16x16x32_bf16 v[18:21], v[138:141], v[166:169], v[18:21]
	v_mfma_f32_16x16x32_bf16 v[14:17], v[130:133], v[178:181], v[14:17]
	v_mfma_f32_16x16x32_bf16 v[26:29], v[138:141], v[178:181], v[26:29]
	v_mfma_f32_16x16x32_bf16 v[22:25], v[130:133], v[182:185], v[22:25]
	v_mfma_f32_16x16x32_bf16 v[38:41], v[138:141], v[182:185], v[38:41]
	v_mfma_f32_16x16x32_bf16 v[10:13], v[134:137], v[170:173], v[10:13]
	v_mfma_f32_16x16x32_bf16 v[6:9], v[142:145], v[170:173], v[4:7]
	v_mfma_f32_16x16x32_bf16 v[2:5], v[134:137], v[174:177], v[0:3]
	v_mfma_f32_16x16x32_bf16 v[18:21], v[142:145], v[174:177], v[18:21]
	v_mfma_f32_16x16x32_bf16 v[14:17], v[134:137], v[186:189], v[14:17]
	v_mfma_f32_16x16x32_bf16 v[26:29], v[142:145], v[186:189], v[26:29]
	v_mfma_f32_16x16x32_bf16 v[22:25], v[134:137], v[190:193], v[22:25]
	v_mfma_f32_16x16x32_bf16 v[38:41], v[142:145], v[190:193], v[38:41]
	v_mfma_f32_16x16x32_bf16 v[34:37], v[146:149], v[162:165], v[34:37]
	v_mfma_f32_16x16x32_bf16 v[30:33], v[154:157], v[162:165], v[30:33]
	v_mfma_f32_16x16x32_bf16 v[42:45], v[146:149], v[166:169], v[42:45]
	v_mfma_f32_16x16x32_bf16 v[46:49], v[154:157], v[166:169], v[46:49]
	v_mfma_f32_16x16x32_bf16 v[50:53], v[146:149], v[178:181], v[50:53]
	v_mfma_f32_16x16x32_bf16 v[54:57], v[154:157], v[178:181], v[54:57]
	v_mfma_f32_16x16x32_bf16 v[58:61], v[146:149], v[182:185], v[58:61]
	v_mfma_f32_16x16x32_bf16 v[62:65], v[154:157], v[182:185], v[62:65]
	v_mfma_f32_16x16x32_bf16 v[34:37], v[150:153], v[170:173], v[34:37]
	v_mfma_f32_16x16x32_bf16 v[30:33], v[158:161], v[170:173], v[30:33]
	v_mfma_f32_16x16x32_bf16 v[42:45], v[150:153], v[174:177], v[42:45]
	v_mfma_f32_16x16x32_bf16 v[46:49], v[158:161], v[174:177], v[46:49]
	v_mfma_f32_16x16x32_bf16 v[50:53], v[150:153], v[186:189], v[50:53]
	v_mfma_f32_16x16x32_bf16 v[54:57], v[158:161], v[186:189], v[54:57]
	v_mfma_f32_16x16x32_bf16 v[58:61], v[150:153], v[190:193], v[58:61]
	v_mfma_f32_16x16x32_bf16 v[62:65], v[158:161], v[190:193], v[62:65]
	s_barrier
	s_setprio 0
	s_add_i32 s4, s4, 2
	s_addk_i32 s5, 0x100
	s_cmp_gt_u32 s4, 61
	s_cbranch_scc0 .LBB0_1251
	s_and_b64 vcc, exec, s[18:19]
	s_cbranch_vccz .LBB0_1254
	s_barrier
